# v014 + hot-loop header code alignment: .p2align 6 before the four GEMM K-loop headers and the forget-prompt / forget-sample attention loops
# baseline (speedup 1.0000x reference)
.LBB0_150:
	s_ashr_i32 s47, s46, 31
	s_lshl_b64 s[8:9], s[46:47], 19
	s_add_u32 s50, s43, s8
	s_addc_u32 s51, s68, s9
	s_and_b64 s[8:9], s[48:49], exec
	s_cselect_b32 s3, s51, s1
	s_cselect_b32 s33, s50, s0
	s_ashr_i32 s45, s44, 31
	s_lshl_b64 s[8:9], s[44:45], 19
	s_add_u32 s52, s69, s8
	s_addc_u32 s53, s70, s9
	s_and_b64 s[8:9], s[48:49], exec
	s_cselect_b32 s45, s53, s7
	s_cselect_b32 s47, s52, s6
	s_add_u32 s0, s0, 0x40080
	s_addc_u32 s1, s1, 0
	s_add_u32 s56, s6, 0x100
	v_mov_b32_e32 v2, 0
	s_addc_u32 s57, s7, 0
	s_mov_b32 s58, -2
	s_waitcnt lgkmcnt(0)
	v_mov_b32_e32 v3, v2
	v_mov_b32_e32 v4, v2
	v_mov_b32_e32 v5, v2
	v_mov_b32_e32 v6, v2
	v_mov_b32_e32 v7, v2
	v_mov_b32_e32 v8, v2
	v_mov_b32_e32 v9, v2
	v_mov_b32_e32 v18, v2
	v_mov_b32_e32 v19, v2
	v_mov_b32_e32 v20, v2
	v_mov_b32_e32 v21, v2
	v_mov_b32_e32 v22, v2
	v_mov_b32_e32 v23, v2
	v_mov_b32_e32 v24, v2
	v_mov_b32_e32 v25, v2
	v_mov_b32_e32 v34, v2
	v_mov_b32_e32 v35, v2
	v_mov_b32_e32 v36, v2
	v_mov_b32_e32 v37, v2
	v_mov_b32_e32 v38, v2
	v_mov_b32_e32 v39, v2
	v_mov_b32_e32 v40, v2
	v_mov_b32_e32 v41, v2
	v_mov_b32_e32 v50, v2
	v_mov_b32_e32 v51, v2
	v_mov_b32_e32 v52, v2
	v_mov_b32_e32 v53, v2
	v_mov_b32_e32 v54, v2
	v_mov_b32_e32 v55, v2
	v_mov_b32_e32 v56, v2
	v_mov_b32_e32 v57, v2
	v_mov_b32_e32 v10, v2
	v_mov_b32_e32 v11, v2
	v_mov_b32_e32 v12, v2
	v_mov_b32_e32 v13, v2
	v_mov_b32_e32 v14, v2
	v_mov_b32_e32 v15, v2
	v_mov_b32_e32 v16, v2
	v_mov_b32_e32 v17, v2
	v_mov_b32_e32 v26, v2
	v_mov_b32_e32 v27, v2
	v_mov_b32_e32 v28, v2
	v_mov_b32_e32 v29, v2
	v_mov_b32_e32 v30, v2
	v_mov_b32_e32 v31, v2
	v_mov_b32_e32 v32, v2
	v_mov_b32_e32 v33, v2
	v_mov_b32_e32 v42, v2
	v_mov_b32_e32 v43, v2
	v_mov_b32_e32 v44, v2
	v_mov_b32_e32 v45, v2
	v_mov_b32_e32 v46, v2
	v_mov_b32_e32 v47, v2
	v_mov_b32_e32 v48, v2
	v_mov_b32_e32 v49, v2
	v_mov_b32_e32 v58, v2
	v_mov_b32_e32 v59, v2
	v_mov_b32_e32 v60, v2
	v_mov_b32_e32 v61, v2
	v_mov_b32_e32 v62, v2
	v_mov_b32_e32 v63, v2
	v_mov_b32_e32 v64, v2
	v_mov_b32_e32 v65, v2
	v_mov_b32_e32 v66, v2
	v_mov_b32_e32 v67, v2
	v_mov_b32_e32 v68, v2
	v_mov_b32_e32 v69, v2
	v_mov_b32_e32 v70, v2
	v_mov_b32_e32 v71, v2
	v_mov_b32_e32 v72, v2
	v_mov_b32_e32 v73, v2
	v_mov_b32_e32 v82, v2
	v_mov_b32_e32 v83, v2
	v_mov_b32_e32 v84, v2
	v_mov_b32_e32 v85, v2
	v_mov_b32_e32 v86, v2
	v_mov_b32_e32 v87, v2
	v_mov_b32_e32 v88, v2
	v_mov_b32_e32 v89, v2
	v_mov_b32_e32 v98, v2
	v_mov_b32_e32 v99, v2
	v_mov_b32_e32 v100, v2
	v_mov_b32_e32 v101, v2
	v_mov_b32_e32 v102, v2
	v_mov_b32_e32 v103, v2
	v_mov_b32_e32 v104, v2
	v_mov_b32_e32 v105, v2
	v_mov_b32_e32 v114, v2
	v_mov_b32_e32 v115, v2
	v_mov_b32_e32 v116, v2
	v_mov_b32_e32 v117, v2
	v_mov_b32_e32 v118, v2
	v_mov_b32_e32 v119, v2
	v_mov_b32_e32 v120, v2
	v_mov_b32_e32 v121, v2
	v_mov_b32_e32 v74, v2
	v_mov_b32_e32 v75, v2
	v_mov_b32_e32 v76, v2
	v_mov_b32_e32 v77, v2
	v_mov_b32_e32 v78, v2
	v_mov_b32_e32 v79, v2
	v_mov_b32_e32 v80, v2
	v_mov_b32_e32 v81, v2
	v_mov_b32_e32 v90, v2
	v_mov_b32_e32 v91, v2
	v_mov_b32_e32 v92, v2
	v_mov_b32_e32 v93, v2
	v_mov_b32_e32 v94, v2
	v_mov_b32_e32 v95, v2
	v_mov_b32_e32 v96, v2
	v_mov_b32_e32 v97, v2
	v_mov_b32_e32 v106, v2
	v_mov_b32_e32 v107, v2
	v_mov_b32_e32 v108, v2
	v_mov_b32_e32 v109, v2
	v_mov_b32_e32 v110, v2
	v_mov_b32_e32 v111, v2
	v_mov_b32_e32 v112, v2
	v_mov_b32_e32 v113, v2
	v_mov_b32_e32 v122, v2
	v_mov_b32_e32 v123, v2
	v_mov_b32_e32 v124, v2
	v_mov_b32_e32 v125, v2
	v_mov_b32_e32 v126, v2
	v_mov_b32_e32 v127, v2
	v_mov_b32_e32 v128, v2
	v_mov_b32_e32 v129, v2
	s_waitcnt vmcnt(0)
	.p2align	6

.LBB0_477:
	s_andn2_b64 vcc, exec, s[70:71]
	s_cbranch_vccz .LBB0_496
	.p2align	6

.LBB0_503:
	v_sub_f32_e32 v2, v219, v5
	v_bfe_u32 v3, v2, 16, 1
	v_add3_u32 v3, v2, v3, s33
	v_and_b32_e32 v5, 0xffff0000, v3
	v_sub_f32_e32 v2, v2, v5
	v_bfe_u32 v5, v2, 16, 1
	v_add3_u32 v5, v2, v5, s33
	v_and_b32_e32 v5, 0xffff0000, v5
	v_sub_f32_e32 v2, v2, v5
	v_bfe_u32 v26, v2, 16, 1
	v_add3_u32 v2, v2, v26, s33
	v_or_b32_sdwa v3, v5, v3 dst_sel:DWORD dst_unused:UNUSED_PAD src0_sel:DWORD src1_sel:WORD_1
	v_lshrrev_b32_e32 v26, 16, v2
	v_cndmask_b32_e64 v2, 0, v3, s[26:27]
	v_mov_b32_e32 v5, v4
	v_cndmask_b32_e64 v3, 0, v26, s[26:27]
	v_cvt_pk_bf16_f32 v62, v62, v63
	v_cvt_pk_bf16_f32 v63, v64, v65
	v_mfma_f32_32x32x16_bf16 v[26:41], v[2:5], v[130:133], 0
	v_cvt_pk_bf16_f32 v64, v58, v59
	v_cvt_pk_bf16_f32 v65, v60, v61
	v_cvt_pk_bf16_f32 v54, v54, v55
	v_cvt_pk_bf16_f32 v55, v56, v57
	v_cvt_pk_bf16_f32 v56, v50, v51
	v_cvt_pk_bf16_f32 v57, v52, v53
	v_cvt_pk_bf16_f32 v46, v46, v47
	v_mfma_f32_32x32x16_bf16 v[26:41], v[62:65], v[94:97], v[26:41]
	v_cvt_pk_bf16_f32 v47, v48, v49
	v_cvt_pk_bf16_f32 v48, v42, v43
	v_cvt_pk_bf16_f32 v49, v44, v45
	v_cvt_pk_bf16_f32 v22, v22, v23
	v_cvt_pk_bf16_f32 v23, v24, v25
	v_cvt_pk_bf16_f32 v24, v18, v19
	v_cvt_pk_bf16_f32 v25, v20, v21
	v_mfma_f32_32x32x16_bf16 v[26:41], v[54:57], v[90:93], v[26:41]
	v_mbcnt_hi_u32_b32 v2, -1, v196
	v_and_b32_e32 v5, 64, v2
	v_xor_b32_e32 v3, 32, v2
	v_add_u32_e32 v5, 64, v5
	v_cmp_lt_i32_e32 vcc, v3, v5
	v_add3_u32 v5, s16, v239, v240
	s_waitcnt lgkmcnt(0)
	v_mfma_f32_32x32x16_bf16 v[26:41], v[46:49], v[86:89], v[26:41]
	v_cndmask_b32_e32 v2, v2, v3, vcc
	v_lshlrev_b32_e32 v217, 2, v2
	v_add_u32_e32 v221, v5, v245
	s_andn2_b64 vcc, exec, s[10:11]
	v_mfma_f32_32x32x16_bf16 v[26:41], v[22:25], v[82:85], v[26:41]
	s_nop 11
	v_max_f32_e32 v2, v27, v27
	v_max_f32_e32 v3, v26, v26
	v_max_f32_e32 v2, v3, v2
	v_max3_f32 v2, v2, v28, v29
	v_max3_f32 v2, v2, v30, v31
	v_max3_f32 v2, v2, v32, v33
	v_max3_f32 v2, v2, v34, v35
	v_max3_f32 v2, v2, v36, v37
	v_max3_f32 v2, v2, v38, v39
	v_max3_f32 v2, v2, v40, v41
	ds_bpermute_b32 v3, v217, v2
	s_waitcnt lgkmcnt(0)
	v_max_f32_e32 v3, v3, v3
	v_max_f32_e32 v2, v2, v3
	v_sub_f32_e32 v22, v33, v2
	v_sub_f32_e32 v23, v32, v2
	v_sub_f32_e32 v18, v31, v2
	v_sub_f32_e32 v19, v30, v2
	v_sub_f32_e32 v20, v29, v2
	v_sub_f32_e32 v21, v28, v2
	v_sub_f32_e32 v24, v27, v2
	v_sub_f32_e32 v25, v26, v2
	v_exp_f32_e32 v5, v23
	v_exp_f32_e32 v22, v22
	v_sub_f32_e32 v3, v41, v2
	v_sub_f32_e32 v54, v40, v2
	v_exp_f32_e32 v25, v25
	v_exp_f32_e32 v24, v24
	v_exp_f32_e32 v26, v21
	v_exp_f32_e32 v27, v20
	v_exp_f32_e32 v28, v19
	v_exp_f32_e32 v29, v18
	ds_read_b64_tr_b16 v[18:19], v221
	ds_read_b64_tr_b16 v[20:21], v221 offset:1152
	ds_read_b64_tr_b16 v[42:43], v221 offset:1216
	ds_read_b64_tr_b16 v[40:41], v221 offset:64
	v_sub_f32_e32 v55, v39, v2
	v_cvt_pk_bf16_f32 v53, v5, v22
	v_sub_f32_e32 v5, v38, v2
	v_sub_f32_e32 v56, v37, v2
	v_sub_f32_e32 v57, v36, v2
	v_cvt_pk_bf16_f32 v50, v25, v24
	v_cvt_pk_bf16_f32 v51, v26, v27
	v_cvt_pk_bf16_f32 v52, v28, v29
	v_sub_f32_e32 v35, v35, v2
	v_sub_f32_e32 v34, v34, v2
	v_exp_f32_e32 v73, v57
	v_exp_f32_e32 v74, v56
	v_exp_f32_e32 v5, v5
	v_exp_f32_e32 v75, v55
	v_exp_f32_e32 v76, v54
	v_exp_f32_e32 v3, v3
	s_waitcnt lgkmcnt(2)
	v_mfma_f32_32x32x16_bf16 v[18:33], v[18:21], v[50:53], 0
	v_exp_f32_e32 v67, v34
	v_exp_f32_e32 v72, v35
	ds_read_b64_tr_b16 v[68:69], v221 offset:2304
	ds_read_b64_tr_b16 v[70:71], v221 offset:3456
	v_cvt_pk_bf16_f32 v73, v73, v74
	v_cvt_pk_bf16_f32 v74, v5, v75
	v_cvt_pk_bf16_f32 v75, v76, v3
	ds_read_b64_tr_b16 v[78:79], v221 offset:3520
	ds_read_b64_tr_b16 v[76:77], v221 offset:2368
	s_waitcnt lgkmcnt(4)
	v_mfma_f32_32x32x16_bf16 v[34:49], v[40:43], v[50:53], 0
	v_cvt_pk_bf16_f32 v72, v67, v72
	s_waitcnt lgkmcnt(0)
	v_add_f32_e32 v211, 0, v2
	v_mfma_f32_32x32x16_bf16 v[50:65], v[134:137], v[50:53], 0
	s_waitcnt lgkmcnt(2)
	v_mfma_f32_32x32x16_bf16 v[18:33], v[68:71], v[72:75], v[18:33]
	s_waitcnt lgkmcnt(0)
	v_mfma_f32_32x32x16_bf16 v[34:49], v[76:79], v[72:75], v[34:49]
	v_mfma_f32_32x32x16_bf16 v[50:65], v[134:137], v[72:75], v[50:65]
	s_cbranch_vccnz .LBB0_511
	v_readlane_b32 s10, v254, 27
	s_add_u32 s10, s10, s17
	v_readlane_b32 s11, v254, 28
	v_add_u32_e32 v2, s18, v251
	v_mov_b32_e32 v3, v4
	s_addc_u32 s11, s11, s7
	v_lshl_add_u64 v[228:229], v[2:3], 2, s[10:11]
	v_lshlrev_b64 v[2:3], 11, v[2:3]
	v_lshl_add_u64 v[2:3], s[8:9], 0, v[2:3]
	s_and_b32 s7, s19, 7
	v_lshl_or_b32 v2, s7, 8, v2
	s_waitcnt vmcnt(12)
	v_mov_b64_e32 v[180:181], v[128:129]
	s_waitcnt vmcnt(11)
	v_mov_b64_e32 v[184:185], v[152:153]
	v_mov_b64_e32 v[172:173], v[124:125]
	v_mov_b64_e32 v[176:177], v[148:149]
	v_mov_b64_e32 v[164:165], v[120:121]
	v_mov_b64_e32 v[168:169], v[144:145]
	s_waitcnt vmcnt(9)
	v_mov_b64_e32 v[188:189], v[160:161]
	v_mov_b64_e32 v[192:193], v[156:157]
	v_lshl_add_u32 v226, s15, 16, v250
	v_lshl_add_u64 v[230:231], v[208:209], 0, v[2:3]
	s_mov_b64 s[8:9], 0
	s_mov_b32 s7, s15
	v_mov_b64_e32 v[178:179], v[126:127]
	v_mov_b64_e32 v[182:183], v[150:151]
	v_mov_b64_e32 v[170:171], v[122:123]
	v_mov_b64_e32 v[174:175], v[146:147]
	v_mov_b64_e32 v[162:163], v[118:119]
	v_mov_b64_e32 v[166:167], v[142:143]
	v_mov_b64_e32 v[186:187], v[158:159]
	v_mov_b64_e32 v[190:191], v[154:155]
	s_waitcnt vmcnt(0)
	v_mov_b32_e32 v223, v66
	.p2align	6

.LBB0_844:
	s_ashr_i32 s19, s18, 31
	s_lshl_b64 s[20:21], s[18:19], 19
	s_add_u32 s20, s33, s20
	s_addc_u32 s21, s36, s21
	s_and_b64 s[22:23], s[4:5], exec
	s_cselect_b32 s19, s21, s29
	s_cselect_b32 s25, s20, s28
	s_ashr_i32 s17, s16, 31
	s_lshl_b64 s[22:23], s[16:17], 19
	s_add_u32 s22, s37, s22
	s_addc_u32 s23, s38, s23
	s_and_b64 s[34:35], s[4:5], exec
	s_cselect_b32 s17, s23, s31
	s_cselect_b32 s51, s22, s30
	s_add_u32 s28, s28, 0x40080
	s_addc_u32 s29, s29, 0
	s_add_u32 s52, s30, 0x100
	v_mov_b32_e32 v2, 0
	s_addc_u32 s53, s31, 0
	s_mov_b32 s54, -2
	s_waitcnt lgkmcnt(0)
	v_mov_b32_e32 v3, v2
	v_mov_b32_e32 v4, v2
	v_mov_b32_e32 v5, v2
	v_mov_b32_e32 v6, v2
	v_mov_b32_e32 v7, v2
	v_mov_b32_e32 v8, v2
	v_mov_b32_e32 v9, v2
	v_mov_b32_e32 v18, v2
	v_mov_b32_e32 v19, v2
	v_mov_b32_e32 v20, v2
	v_mov_b32_e32 v21, v2
	v_mov_b32_e32 v22, v2
	v_mov_b32_e32 v23, v2
	v_mov_b32_e32 v24, v2
	v_mov_b32_e32 v25, v2
	v_mov_b32_e32 v34, v2
	v_mov_b32_e32 v35, v2
	v_mov_b32_e32 v36, v2
	v_mov_b32_e32 v37, v2
	v_mov_b32_e32 v38, v2
	v_mov_b32_e32 v39, v2
	v_mov_b32_e32 v40, v2
	v_mov_b32_e32 v41, v2
	v_mov_b32_e32 v50, v2
	v_mov_b32_e32 v51, v2
	v_mov_b32_e32 v52, v2
	v_mov_b32_e32 v53, v2
	v_mov_b32_e32 v54, v2
	v_mov_b32_e32 v55, v2
	v_mov_b32_e32 v56, v2
	v_mov_b32_e32 v57, v2
	v_mov_b32_e32 v10, v2
	v_mov_b32_e32 v11, v2
	v_mov_b32_e32 v12, v2
	v_mov_b32_e32 v13, v2
	v_mov_b32_e32 v14, v2
	v_mov_b32_e32 v15, v2
	v_mov_b32_e32 v16, v2
	v_mov_b32_e32 v17, v2
	v_mov_b32_e32 v26, v2
	v_mov_b32_e32 v27, v2
	v_mov_b32_e32 v28, v2
	v_mov_b32_e32 v29, v2
	v_mov_b32_e32 v30, v2
	v_mov_b32_e32 v31, v2
	v_mov_b32_e32 v32, v2
	v_mov_b32_e32 v33, v2
	v_mov_b32_e32 v42, v2
	v_mov_b32_e32 v43, v2
	v_mov_b32_e32 v44, v2
	v_mov_b32_e32 v45, v2
	v_mov_b32_e32 v46, v2
	v_mov_b32_e32 v47, v2
	v_mov_b32_e32 v48, v2
	v_mov_b32_e32 v49, v2
	v_mov_b32_e32 v58, v2
	v_mov_b32_e32 v59, v2
	v_mov_b32_e32 v60, v2
	v_mov_b32_e32 v61, v2
	v_mov_b32_e32 v62, v2
	v_mov_b32_e32 v63, v2
	v_mov_b32_e32 v64, v2
	v_mov_b32_e32 v65, v2
	v_mov_b32_e32 v66, v2
	v_mov_b32_e32 v67, v2
	v_mov_b32_e32 v68, v2
	v_mov_b32_e32 v69, v2
	v_mov_b32_e32 v70, v2
	v_mov_b32_e32 v71, v2
	v_mov_b32_e32 v72, v2
	v_mov_b32_e32 v73, v2
	v_mov_b32_e32 v82, v2
	v_mov_b32_e32 v83, v2
	v_mov_b32_e32 v84, v2
	v_mov_b32_e32 v85, v2
	v_mov_b32_e32 v86, v2
	v_mov_b32_e32 v87, v2
	v_mov_b32_e32 v88, v2
	v_mov_b32_e32 v89, v2
	v_mov_b32_e32 v98, v2
	v_mov_b32_e32 v99, v2
	v_mov_b32_e32 v100, v2
	v_mov_b32_e32 v101, v2
	v_mov_b32_e32 v102, v2
	v_mov_b32_e32 v103, v2
	v_mov_b32_e32 v104, v2
	v_mov_b32_e32 v105, v2
	v_mov_b32_e32 v114, v2
	v_mov_b32_e32 v115, v2
	v_mov_b32_e32 v116, v2
	v_mov_b32_e32 v117, v2
	v_mov_b32_e32 v118, v2
	v_mov_b32_e32 v119, v2
	v_mov_b32_e32 v120, v2
	v_mov_b32_e32 v121, v2
	v_mov_b32_e32 v74, v2
	v_mov_b32_e32 v75, v2
	v_mov_b32_e32 v76, v2
	v_mov_b32_e32 v77, v2
	v_mov_b32_e32 v78, v2
	v_mov_b32_e32 v79, v2
	v_mov_b32_e32 v80, v2
	v_mov_b32_e32 v81, v2
	v_mov_b32_e32 v90, v2
	v_mov_b32_e32 v91, v2
	v_mov_b32_e32 v92, v2
	v_mov_b32_e32 v93, v2
	v_mov_b32_e32 v94, v2
	v_mov_b32_e32 v95, v2
	v_mov_b32_e32 v96, v2
	v_mov_b32_e32 v97, v2
	v_mov_b32_e32 v106, v2
	v_mov_b32_e32 v107, v2
	v_mov_b32_e32 v108, v2
	v_mov_b32_e32 v109, v2
	v_mov_b32_e32 v110, v2
	v_mov_b32_e32 v111, v2
	v_mov_b32_e32 v112, v2
	v_mov_b32_e32 v113, v2
	v_mov_b32_e32 v122, v2
	v_mov_b32_e32 v123, v2
	v_mov_b32_e32 v124, v2
	v_mov_b32_e32 v125, v2
	v_mov_b32_e32 v126, v2
	v_mov_b32_e32 v127, v2
	v_mov_b32_e32 v128, v2
	v_mov_b32_e32 v129, v2
	.p2align	6

.LBB0_955:
	s_ashr_i32 s29, s28, 31
	s_lshl_b64 s[30:31], s[28:29], 19
	s_add_u32 s30, s40, s30
	s_addc_u32 s31, s41, s31
	s_and_b64 s[34:35], s[0:1], exec
	s_cselect_b32 s29, s31, s7
	s_cselect_b32 s61, s30, s6
	s_ashr_i32 s27, s26, 31
	s_lshl_b64 s[34:35], s[26:27], 19
	s_add_u32 s34, s42, s34
	s_addc_u32 s35, s43, s35
	s_and_b64 s[38:39], s[0:1], exec
	s_cselect_b32 s27, s35, s37
	s_cselect_b32 s62, s34, s36
	s_add_u32 s6, s6, 0x40080
	s_addc_u32 s7, s7, 0
	s_add_u32 s63, s36, 0x100
	v_mov_b32_e32 v2, 0
	s_addc_u32 s64, s37, 0
	s_mov_b32 s65, -2
	v_mov_b32_e32 v3, v2
	v_mov_b32_e32 v4, v2
	v_mov_b32_e32 v5, v2
	v_mov_b32_e32 v6, v2
	v_mov_b32_e32 v7, v2
	v_mov_b32_e32 v8, v2
	v_mov_b32_e32 v9, v2
	v_mov_b32_e32 v18, v2
	v_mov_b32_e32 v19, v2
	v_mov_b32_e32 v20, v2
	v_mov_b32_e32 v21, v2
	v_mov_b32_e32 v22, v2
	v_mov_b32_e32 v23, v2
	v_mov_b32_e32 v24, v2
	v_mov_b32_e32 v25, v2
	v_mov_b32_e32 v34, v2
	v_mov_b32_e32 v35, v2
	v_mov_b32_e32 v36, v2
	v_mov_b32_e32 v37, v2
	v_mov_b32_e32 v38, v2
	v_mov_b32_e32 v39, v2
	v_mov_b32_e32 v40, v2
	v_mov_b32_e32 v41, v2
	v_mov_b32_e32 v50, v2
	v_mov_b32_e32 v51, v2
	v_mov_b32_e32 v52, v2
	v_mov_b32_e32 v53, v2
	v_mov_b32_e32 v54, v2
	v_mov_b32_e32 v55, v2
	v_mov_b32_e32 v56, v2
	v_mov_b32_e32 v57, v2
	v_mov_b32_e32 v10, v2
	v_mov_b32_e32 v11, v2
	v_mov_b32_e32 v12, v2
	v_mov_b32_e32 v13, v2
	v_mov_b32_e32 v14, v2
	v_mov_b32_e32 v15, v2
	v_mov_b32_e32 v16, v2
	v_mov_b32_e32 v17, v2
	v_mov_b32_e32 v26, v2
	v_mov_b32_e32 v27, v2
	v_mov_b32_e32 v28, v2
	v_mov_b32_e32 v29, v2
	v_mov_b32_e32 v30, v2
	v_mov_b32_e32 v31, v2
	v_mov_b32_e32 v32, v2
	v_mov_b32_e32 v33, v2
	v_mov_b32_e32 v42, v2
	v_mov_b32_e32 v43, v2
	v_mov_b32_e32 v44, v2
	v_mov_b32_e32 v45, v2
	v_mov_b32_e32 v46, v2
	v_mov_b32_e32 v47, v2
	v_mov_b32_e32 v48, v2
	v_mov_b32_e32 v49, v2
	v_mov_b32_e32 v58, v2
	v_mov_b32_e32 v59, v2
	v_mov_b32_e32 v60, v2
	v_mov_b32_e32 v61, v2
	v_mov_b32_e32 v62, v2
	v_mov_b32_e32 v63, v2
	v_mov_b32_e32 v64, v2
	v_mov_b32_e32 v65, v2
	v_mov_b32_e32 v66, v2
	v_mov_b32_e32 v67, v2
	v_mov_b32_e32 v68, v2
	v_mov_b32_e32 v69, v2
	v_mov_b32_e32 v70, v2
	v_mov_b32_e32 v71, v2
	v_mov_b32_e32 v72, v2
	v_mov_b32_e32 v73, v2
	v_mov_b32_e32 v82, v2
	v_mov_b32_e32 v83, v2
	v_mov_b32_e32 v84, v2
	v_mov_b32_e32 v85, v2
	v_mov_b32_e32 v86, v2
	v_mov_b32_e32 v87, v2
	v_mov_b32_e32 v88, v2
	v_mov_b32_e32 v89, v2
	v_mov_b32_e32 v98, v2
	v_mov_b32_e32 v99, v2
	v_mov_b32_e32 v100, v2
	v_mov_b32_e32 v101, v2
	v_mov_b32_e32 v102, v2
	v_mov_b32_e32 v103, v2
	v_mov_b32_e32 v104, v2
	v_mov_b32_e32 v105, v2
	v_mov_b32_e32 v114, v2
	v_mov_b32_e32 v115, v2
	v_mov_b32_e32 v116, v2
	v_mov_b32_e32 v117, v2
	v_mov_b32_e32 v118, v2
	v_mov_b32_e32 v119, v2
	v_mov_b32_e32 v120, v2
	v_mov_b32_e32 v121, v2
	v_mov_b32_e32 v74, v2
	v_mov_b32_e32 v75, v2
	v_mov_b32_e32 v76, v2
	v_mov_b32_e32 v77, v2
	v_mov_b32_e32 v78, v2
	v_mov_b32_e32 v79, v2
	v_mov_b32_e32 v80, v2
	v_mov_b32_e32 v81, v2
	v_mov_b32_e32 v90, v2
	v_mov_b32_e32 v91, v2
	v_mov_b32_e32 v92, v2
	v_mov_b32_e32 v93, v2
	v_mov_b32_e32 v94, v2
	v_mov_b32_e32 v95, v2
	v_mov_b32_e32 v96, v2
	v_mov_b32_e32 v97, v2
	v_mov_b32_e32 v106, v2
	v_mov_b32_e32 v107, v2
	v_mov_b32_e32 v108, v2
	v_mov_b32_e32 v109, v2
	v_mov_b32_e32 v110, v2
	v_mov_b32_e32 v111, v2
	v_mov_b32_e32 v112, v2
	v_mov_b32_e32 v113, v2
	v_mov_b32_e32 v122, v2
	v_mov_b32_e32 v123, v2
	v_mov_b32_e32 v124, v2
	v_mov_b32_e32 v125, v2
	v_mov_b32_e32 v126, v2
	v_mov_b32_e32 v127, v2
	v_mov_b32_e32 v128, v2
	v_mov_b32_e32 v129, v2
	.p2align	6

.LBB0_1050:
	s_ashr_i32 s13, s12, 31
	s_lshl_b64 s[14:15], s[12:13], 21
	s_add_u32 s14, s27, s14
	s_addc_u32 s15, s28, s15
	s_and_b64 s[16:17], s[0:1], exec
	s_cselect_b32 s13, s15, s21
	s_cselect_b32 s43, s14, s20
	s_ashr_i32 s11, s10, 31
	s_lshl_b64 s[16:17], s[10:11], 21
	s_add_u32 s16, s29, s16
	s_addc_u32 s17, s30, s17
	s_and_b64 s[24:25], s[0:1], exec
	s_cselect_b32 s11, s17, s23
	s_cselect_b32 s44, s16, s22
	s_add_u32 s20, s20, 0x100080
	s_addc_u32 s21, s21, 0
	s_add_u32 s45, s22, 0x100
	v_mov_b32_e32 v0, 0
	s_addc_u32 s46, s23, 0
	s_mov_b32 s47, -2
	v_mov_b32_e32 v1, v0
	v_mov_b32_e32 v2, v0
	v_mov_b32_e32 v3, v0
	v_mov_b32_e32 v4, v0
	v_mov_b32_e32 v5, v0
	v_mov_b32_e32 v6, v0
	v_mov_b32_e32 v7, v0
	v_mov_b32_e32 v16, v0
	v_mov_b32_e32 v17, v0
	v_mov_b32_e32 v18, v0
	v_mov_b32_e32 v19, v0
	v_mov_b32_e32 v20, v0
	v_mov_b32_e32 v21, v0
	v_mov_b32_e32 v22, v0
	v_mov_b32_e32 v23, v0
	v_mov_b32_e32 v32, v0
	v_mov_b32_e32 v33, v0
	v_mov_b32_e32 v34, v0
	v_mov_b32_e32 v35, v0
	v_mov_b32_e32 v36, v0
	v_mov_b32_e32 v37, v0
	v_mov_b32_e32 v38, v0
	v_mov_b32_e32 v39, v0
	v_mov_b32_e32 v48, v0
	v_mov_b32_e32 v49, v0
	v_mov_b32_e32 v50, v0
	v_mov_b32_e32 v51, v0
	v_mov_b32_e32 v52, v0
	v_mov_b32_e32 v53, v0
	v_mov_b32_e32 v54, v0
	v_mov_b32_e32 v55, v0
	v_mov_b32_e32 v8, v0
	v_mov_b32_e32 v9, v0
	v_mov_b32_e32 v10, v0
	v_mov_b32_e32 v11, v0
	v_mov_b32_e32 v12, v0
	v_mov_b32_e32 v13, v0
	v_mov_b32_e32 v14, v0
	v_mov_b32_e32 v15, v0
	v_mov_b32_e32 v24, v0
	v_mov_b32_e32 v25, v0
	v_mov_b32_e32 v26, v0
	v_mov_b32_e32 v27, v0
	v_mov_b32_e32 v28, v0
	v_mov_b32_e32 v29, v0
	v_mov_b32_e32 v30, v0
	v_mov_b32_e32 v31, v0
	v_mov_b32_e32 v40, v0
	v_mov_b32_e32 v41, v0
	v_mov_b32_e32 v42, v0
	v_mov_b32_e32 v43, v0
	v_mov_b32_e32 v44, v0
	v_mov_b32_e32 v45, v0
	v_mov_b32_e32 v46, v0
	v_mov_b32_e32 v47, v0
	v_mov_b32_e32 v56, v0
	v_mov_b32_e32 v57, v0
	v_mov_b32_e32 v58, v0
	v_mov_b32_e32 v59, v0
	v_mov_b32_e32 v60, v0
	v_mov_b32_e32 v61, v0
	v_mov_b32_e32 v62, v0
	v_mov_b32_e32 v63, v0
	v_mov_b32_e32 v64, v0
	v_mov_b32_e32 v65, v0
	v_mov_b32_e32 v66, v0
	v_mov_b32_e32 v67, v0
	v_mov_b32_e32 v68, v0
	v_mov_b32_e32 v69, v0
	v_mov_b32_e32 v70, v0
	v_mov_b32_e32 v71, v0
	v_mov_b32_e32 v80, v0
	v_mov_b32_e32 v81, v0
	v_mov_b32_e32 v82, v0
	v_mov_b32_e32 v83, v0
	v_mov_b32_e32 v84, v0
	v_mov_b32_e32 v85, v0
	v_mov_b32_e32 v86, v0
	v_mov_b32_e32 v87, v0
	v_mov_b32_e32 v96, v0
	v_mov_b32_e32 v97, v0
	v_mov_b32_e32 v98, v0
	v_mov_b32_e32 v99, v0
	v_mov_b32_e32 v100, v0
	v_mov_b32_e32 v101, v0
	v_mov_b32_e32 v102, v0
	v_mov_b32_e32 v103, v0
	v_mov_b32_e32 v112, v0
	v_mov_b32_e32 v113, v0
	v_mov_b32_e32 v114, v0
	v_mov_b32_e32 v115, v0
	v_mov_b32_e32 v116, v0
	v_mov_b32_e32 v117, v0
	v_mov_b32_e32 v118, v0
	v_mov_b32_e32 v119, v0
	v_mov_b32_e32 v72, v0
	v_mov_b32_e32 v73, v0
	v_mov_b32_e32 v74, v0
	v_mov_b32_e32 v75, v0
	v_mov_b32_e32 v76, v0
	v_mov_b32_e32 v77, v0
	v_mov_b32_e32 v78, v0
	v_mov_b32_e32 v79, v0
	v_mov_b32_e32 v88, v0
	v_mov_b32_e32 v89, v0
	v_mov_b32_e32 v90, v0
	v_mov_b32_e32 v91, v0
	v_mov_b32_e32 v92, v0
	v_mov_b32_e32 v93, v0
	v_mov_b32_e32 v94, v0
	v_mov_b32_e32 v95, v0
	v_mov_b32_e32 v104, v0
	v_mov_b32_e32 v105, v0
	v_mov_b32_e32 v106, v0
	v_mov_b32_e32 v107, v0
	v_mov_b32_e32 v108, v0
	v_mov_b32_e32 v109, v0
	v_mov_b32_e32 v110, v0
	v_mov_b32_e32 v111, v0
	v_mov_b32_e32 v120, v0
	v_mov_b32_e32 v121, v0
	v_mov_b32_e32 v122, v0
	v_mov_b32_e32 v123, v0
	v_mov_b32_e32 v124, v0
	v_mov_b32_e32 v125, v0
	v_mov_b32_e32 v126, v0
	v_mov_b32_e32 v127, v0
	.p2align	6
